# v23: v22 + no acquire before the mixer unit (the Z rows it loads lie in panels whose slot this CU never loaded from: kind 2's H panel is always a different panel)
# speedup vs baseline: 1.0075x; 1.0016x over previous
.LBB0_501:
	s_or_b64 exec, exec, s[2:3]
	s_waitcnt vmcnt(0)
	s_waitcnt vmcnt(0)
